# grid barrier: leader releases its XCD before its own L1 invalidate; non-leaders invalidate right after arriving, before polling
# speedup vs baseline: 1.0227x; 1.0131x over previous
.LBB0_101:
	s_or_b64 exec, exec, s[8:9]
	v_cvt_f32_u32_e32 v4, v2
	s_waitcnt vmcnt(0)
	v_readfirstlane_b32 s3, v3
	v_sub_u32_e32 v3, 0, v2
	v_rcp_iflag_f32_e32 v4, v4
	v_add_u32_e32 v5, s3, v1
	v_mul_f32_e32 v4, 0x4f7ffffe, v4
	v_cvt_u32_f32_e32 v4, v4
	v_mul_lo_u32 v1, v3, v4
	v_mul_hi_u32 v1, v4, v1
	v_add_u32_e32 v1, v4, v1
	v_mul_hi_u32 v1, v5, v1
	v_mul_lo_u32 v3, v1, v2
	v_sub_u32_e32 v3, v5, v3
	v_add_u32_e32 v4, 1, v1
	v_sub_u32_e32 v6, v3, v2
	v_cmp_ge_u32_e32 vcc, v3, v2
	s_nop 1
	v_cndmask_b32_e32 v1, v1, v4, vcc
	v_cndmask_b32_e32 v3, v3, v6, vcc
	v_add_u32_e32 v4, 1, v1
	v_cmp_ge_u32_e32 vcc, v3, v2
	v_add_u32_e32 v3, 1, v5
	s_nop 0
	v_cndmask_b32_e32 v1, v1, v4, vcc
	v_mul_lo_u32 v4, v2, v1
	v_add_u32_e32 v2, v4, v2
	v_cmp_ne_u32_e32 vcc, v3, v2
	s_and_saveexec_b64 s[8:9], vcc
	s_xor_b64 s[8:9], exec, s[8:9]
	s_cbranch_execz .LBB0_115
	s_waitcnt lgkmcnt(0)
	v_mov_b32_e32 v0, 0
	buffer_inv sc1
	global_load_dword v2, v0, s[88:89] sc1
	s_waitcnt vmcnt(0)
	v_cmp_eq_u32_e32 vcc, v2, v1
	s_and_saveexec_b64 s[10:11], vcc
	s_cbranch_execz .LBB0_114
	s_mov_b32 s3, 1
	s_mov_b64 s[38:39], 0
	s_branch .LBB0_105

.LBB0_114:
	s_or_b64 exec, exec, s[10:11]
	s_waitcnt vmcnt(0)
	s_waitcnt vmcnt(0)

.LBB0_132:
	s_or_b64 exec, exec, s[8:9]
	s_mov_b64 s[8:9], exec
	v_mbcnt_lo_u32_b32 v0, s8, 0
	v_mbcnt_hi_u32_b32 v0, s9, v0
	v_cmp_eq_u32_e32 vcc, 0, v0
	s_waitcnt vmcnt(0)
	s_and_saveexec_b64 s[10:11], vcc
	s_cbranch_execz .LBB0_134
	s_bcnt1_i32_b64 s3, s[8:9]
	v_mov_b32_e32 v0, 0
	v_mov_b32_e32 v1, s3
	global_atomic_add v0, v1, s[88:89]
.LBB0_134:
	s_or_b64 exec, exec, s[10:11]
	buffer_inv sc1
	s_waitcnt vmcnt(0)

.LBB0_635:
	s_or_b64 exec, exec, s[8:9]
	v_cvt_f32_u32_e32 v4, v2
	s_waitcnt vmcnt(0)
	v_readfirstlane_b32 s8, v3
	v_sub_u32_e32 v3, 0, v2
	v_rcp_iflag_f32_e32 v4, v4
	v_add_u32_e32 v5, s8, v1
	v_mul_f32_e32 v4, 0x4f7ffffe, v4
	v_cvt_u32_f32_e32 v4, v4
	v_mul_lo_u32 v1, v3, v4
	v_mul_hi_u32 v1, v4, v1
	v_add_u32_e32 v1, v4, v1
	v_mul_hi_u32 v1, v5, v1
	v_mul_lo_u32 v3, v1, v2
	v_sub_u32_e32 v3, v5, v3
	v_add_u32_e32 v4, 1, v1
	v_cmp_ge_u32_e32 vcc, v3, v2
	s_nop 1
	v_cndmask_b32_e32 v1, v1, v4, vcc
	v_sub_u32_e32 v4, v3, v2
	v_cndmask_b32_e32 v3, v3, v4, vcc
	v_add_u32_e32 v4, 1, v1
	v_cmp_ge_u32_e32 vcc, v3, v2
	v_add_u32_e32 v3, 1, v5
	s_nop 0
	v_cndmask_b32_e32 v1, v1, v4, vcc
	v_mul_lo_u32 v4, v2, v1
	v_add_u32_e32 v2, v4, v2
	v_cmp_ne_u32_e32 vcc, v3, v2
	s_and_saveexec_b64 s[8:9], vcc
	s_xor_b64 s[8:9], exec, s[8:9]
	s_cbranch_execz .LBB0_649
	s_waitcnt lgkmcnt(0)
	v_mov_b32_e32 v0, 0
	buffer_inv sc1
	global_load_dword v2, v0, s[88:89] sc1
	s_waitcnt vmcnt(0)
	v_cmp_eq_u32_e32 vcc, v2, v1
	s_and_saveexec_b64 s[10:11], vcc
	s_cbranch_execz .LBB0_648
	s_mov_b32 s20, 1
	s_mov_b64 s[38:39], 0
	s_branch .LBB0_639

.LBB0_666:
	s_or_b64 exec, exec, s[8:9]
	s_mov_b64 s[8:9], exec
	v_mbcnt_lo_u32_b32 v0, s8, 0
	v_mbcnt_hi_u32_b32 v0, s9, v0
	v_cmp_eq_u32_e32 vcc, 0, v0
	s_waitcnt vmcnt(0)
	s_and_saveexec_b64 s[10:11], vcc
	s_cbranch_execz .LBB0_668
	s_bcnt1_i32_b64 s8, s[8:9]
	v_mov_b32_e32 v0, 0
	v_mov_b32_e32 v1, s8
	global_atomic_add v0, v1, s[88:89]

.LBB0_809:
	s_or_b64 exec, exec, s[8:9]
	v_cvt_f32_u32_e32 v4, v2
	s_waitcnt vmcnt(0)
	v_readfirstlane_b32 s8, v3
	v_sub_u32_e32 v3, 0, v2
	v_rcp_iflag_f32_e32 v4, v4
	v_add_u32_e32 v5, s8, v1
	v_mul_f32_e32 v4, 0x4f7ffffe, v4
	v_cvt_u32_f32_e32 v4, v4
	v_mul_lo_u32 v1, v3, v4
	v_mul_hi_u32 v1, v4, v1
	v_add_u32_e32 v1, v4, v1
	v_mul_hi_u32 v1, v5, v1
	v_mul_lo_u32 v3, v1, v2
	v_sub_u32_e32 v3, v5, v3
	v_add_u32_e32 v4, 1, v1
	v_cmp_ge_u32_e32 vcc, v3, v2
	s_nop 1
	v_cndmask_b32_e32 v1, v1, v4, vcc
	v_sub_u32_e32 v4, v3, v2
	v_cndmask_b32_e32 v3, v3, v4, vcc
	v_add_u32_e32 v4, 1, v1
	v_cmp_ge_u32_e32 vcc, v3, v2
	v_add_u32_e32 v3, 1, v5
	s_nop 0
	v_cndmask_b32_e32 v1, v1, v4, vcc
	v_mul_lo_u32 v4, v2, v1
	v_add_u32_e32 v2, v4, v2
	v_cmp_ne_u32_e32 vcc, v3, v2
	s_and_saveexec_b64 s[8:9], vcc
	s_xor_b64 s[8:9], exec, s[8:9]
	s_cbranch_execz .LBB0_823
	s_waitcnt lgkmcnt(0)
	v_mov_b32_e32 v0, 0
	buffer_inv sc1
	global_load_dword v2, v0, s[88:89] sc1
	s_waitcnt vmcnt(0)
	v_cmp_eq_u32_e32 vcc, v2, v1
	s_and_saveexec_b64 s[10:11], vcc
	s_cbranch_execz .LBB0_822
	s_mov_b32 s20, 1
	s_mov_b64 s[14:15], 0
	s_branch .LBB0_813

.LBB0_877:
	s_or_b64 exec, exec, s[8:9]
	v_cvt_f32_u32_e32 v4, v2
	s_waitcnt vmcnt(0)
	v_readfirstlane_b32 s8, v3
	v_sub_u32_e32 v3, 0, v2
	v_rcp_iflag_f32_e32 v4, v4
	v_add_u32_e32 v5, s8, v1
	v_mul_f32_e32 v4, 0x4f7ffffe, v4
	v_cvt_u32_f32_e32 v4, v4
	v_mul_lo_u32 v1, v3, v4
	v_mul_hi_u32 v1, v4, v1
	v_add_u32_e32 v1, v4, v1
	v_mul_hi_u32 v1, v5, v1
	v_mul_lo_u32 v3, v1, v2
	v_sub_u32_e32 v3, v5, v3
	v_add_u32_e32 v4, 1, v1
	v_cmp_ge_u32_e32 vcc, v3, v2
	s_nop 1
	v_cndmask_b32_e32 v1, v1, v4, vcc
	v_sub_u32_e32 v4, v3, v2
	v_cndmask_b32_e32 v3, v3, v4, vcc
	v_add_u32_e32 v4, 1, v1
	v_cmp_ge_u32_e32 vcc, v3, v2
	v_add_u32_e32 v3, 1, v5
	s_nop 0
	v_cndmask_b32_e32 v1, v1, v4, vcc
	v_mul_lo_u32 v4, v2, v1
	v_add_u32_e32 v2, v4, v2
	v_cmp_ne_u32_e32 vcc, v3, v2
	s_and_saveexec_b64 s[8:9], vcc
	s_xor_b64 s[8:9], exec, s[8:9]
	s_cbranch_execz .LBB0_891
	s_waitcnt lgkmcnt(0)
	v_mov_b32_e32 v0, 0
	buffer_inv sc1
	global_load_dword v2, v0, s[68:69] sc1
	s_waitcnt vmcnt(0)
	v_cmp_eq_u32_e32 vcc, v2, v1
	s_and_saveexec_b64 s[10:11], vcc
	s_cbranch_execz .LBB0_890
	s_mov_b32 s20, 1
	s_mov_b64 s[14:15], 0
	s_branch .LBB0_881

.LBB0_908:
	s_or_b64 exec, exec, s[8:9]
	s_mov_b64 s[8:9], exec
	v_mbcnt_lo_u32_b32 v0, s8, 0
	v_mbcnt_hi_u32_b32 v0, s9, v0
	v_cmp_eq_u32_e32 vcc, 0, v0
	s_waitcnt vmcnt(0)
	s_and_saveexec_b64 s[10:11], vcc
	s_cbranch_execz .LBB0_910
	s_bcnt1_i32_b64 s8, s[8:9]
	v_mov_b32_e32 v0, 0
	v_mov_b32_e32 v1, s8
	global_atomic_add v0, v1, s[68:69]

.LBB0_952:
	s_or_b64 exec, exec, s[8:9]
	v_cvt_f32_u32_e32 v4, v2
	s_waitcnt vmcnt(0)
	v_readfirstlane_b32 s8, v3
	v_sub_u32_e32 v3, 0, v2
	v_rcp_iflag_f32_e32 v4, v4
	v_add_u32_e32 v5, s8, v1
	v_mul_f32_e32 v4, 0x4f7ffffe, v4
	v_cvt_u32_f32_e32 v4, v4
	v_mul_lo_u32 v1, v3, v4
	v_mul_hi_u32 v1, v4, v1
	v_add_u32_e32 v1, v4, v1
	v_mul_hi_u32 v1, v5, v1
	v_mul_lo_u32 v3, v1, v2
	v_sub_u32_e32 v3, v5, v3
	v_add_u32_e32 v4, 1, v1
	v_cmp_ge_u32_e32 vcc, v3, v2
	s_nop 1
	v_cndmask_b32_e32 v1, v1, v4, vcc
	v_sub_u32_e32 v4, v3, v2
	v_cndmask_b32_e32 v3, v3, v4, vcc
	v_add_u32_e32 v4, 1, v1
	v_cmp_ge_u32_e32 vcc, v3, v2
	v_add_u32_e32 v3, 1, v5
	s_nop 0
	v_cndmask_b32_e32 v1, v1, v4, vcc
	v_mul_lo_u32 v4, v2, v1
	v_add_u32_e32 v2, v4, v2
	v_cmp_ne_u32_e32 vcc, v3, v2
	s_and_saveexec_b64 s[8:9], vcc
	s_xor_b64 s[8:9], exec, s[8:9]
	s_cbranch_execz .LBB0_966
	s_waitcnt lgkmcnt(0)
	v_mov_b32_e32 v0, 0
	buffer_inv sc1
	global_load_dword v2, v0, s[68:69] sc1
	s_waitcnt vmcnt(0)
	v_cmp_eq_u32_e32 vcc, v2, v1
	s_and_saveexec_b64 s[10:11], vcc
	s_cbranch_execz .LBB0_965
	s_mov_b32 s15, 1
	s_mov_b64 s[38:39], 0
	s_branch .LBB0_956

.LBB0_1019:
	s_or_b64 exec, exec, s[4:5]
	v_cvt_f32_u32_e32 v4, v2
	s_waitcnt vmcnt(0)
	v_readfirstlane_b32 s4, v3
	v_sub_u32_e32 v3, 0, v2
	v_rcp_iflag_f32_e32 v4, v4
	v_add_u32_e32 v5, s4, v1
	v_mul_f32_e32 v4, 0x4f7ffffe, v4
	v_cvt_u32_f32_e32 v4, v4
	v_mul_lo_u32 v1, v3, v4
	v_mul_hi_u32 v1, v4, v1
	v_add_u32_e32 v1, v4, v1
	v_mul_hi_u32 v1, v5, v1
	v_mul_lo_u32 v3, v1, v2
	v_sub_u32_e32 v3, v5, v3
	v_add_u32_e32 v4, 1, v1
	v_cmp_ge_u32_e32 vcc, v3, v2
	s_nop 1
	v_cndmask_b32_e32 v1, v1, v4, vcc
	v_sub_u32_e32 v4, v3, v2
	v_cndmask_b32_e32 v3, v3, v4, vcc
	v_add_u32_e32 v4, 1, v1
	v_cmp_ge_u32_e32 vcc, v3, v2
	v_add_u32_e32 v3, 1, v5
	s_nop 0
	v_cndmask_b32_e32 v1, v1, v4, vcc
	v_mul_lo_u32 v4, v2, v1
	v_add_u32_e32 v2, v4, v2
	v_cmp_ne_u32_e32 vcc, v3, v2
	s_and_saveexec_b64 s[4:5], vcc
	s_xor_b64 s[4:5], exec, s[4:5]
	s_cbranch_execz .LBB0_1033
	s_waitcnt lgkmcnt(0)
	v_mov_b32_e32 v0, 0
	buffer_inv sc1
	global_load_dword v2, v0, s[68:69] sc1
	s_waitcnt vmcnt(0)
	v_cmp_eq_u32_e32 vcc, v2, v1
	s_and_saveexec_b64 s[6:7], vcc
	s_cbranch_execz .LBB0_1032
	s_mov_b32 s15, 1
	s_mov_b64 s[8:9], 0
	s_branch .LBB0_1023

.LBB0_1032:
	s_or_b64 exec, exec, s[6:7]
	s_waitcnt vmcnt(0)
	s_waitcnt vmcnt(0)

.LBB0_1050:
	s_or_b64 exec, exec, s[4:5]
	s_mov_b64 s[4:5], exec
	v_mbcnt_lo_u32_b32 v0, s4, 0
	v_mbcnt_hi_u32_b32 v0, s5, v0
	v_cmp_eq_u32_e32 vcc, 0, v0
	s_waitcnt vmcnt(0)
	s_and_saveexec_b64 s[6:7], vcc
	s_cbranch_execz .LBB0_1052
	s_bcnt1_i32_b64 s4, s[4:5]
	v_mov_b32_e32 v0, 0
	v_mov_b32_e32 v1, s4
	global_atomic_add v0, v1, s[68:69]
.LBB0_1052:
	s_or_b64 exec, exec, s[6:7]
	buffer_inv sc1
	s_waitcnt vmcnt(0)

.LBB0_1480:
	s_or_b64 exec, exec, s[2:3]
	v_cvt_f32_u32_e32 v4, v2
	s_waitcnt vmcnt(0)
	v_readfirstlane_b32 s2, v3
	v_sub_u32_e32 v3, 0, v2
	v_rcp_iflag_f32_e32 v4, v4
	v_add_u32_e32 v5, s2, v1
	v_mul_f32_e32 v4, 0x4f7ffffe, v4
	v_cvt_u32_f32_e32 v4, v4
	v_mul_lo_u32 v1, v3, v4
	v_mul_hi_u32 v1, v4, v1
	v_add_u32_e32 v1, v4, v1
	v_mul_hi_u32 v1, v5, v1
	v_mul_lo_u32 v3, v1, v2
	v_sub_u32_e32 v3, v5, v3
	v_add_u32_e32 v4, 1, v1
	v_cmp_ge_u32_e32 vcc, v3, v2
	s_nop 1
	v_cndmask_b32_e32 v1, v1, v4, vcc
	v_sub_u32_e32 v4, v3, v2
	v_cndmask_b32_e32 v3, v3, v4, vcc
	v_add_u32_e32 v4, 1, v1
	v_cmp_ge_u32_e32 vcc, v3, v2
	v_add_u32_e32 v3, 1, v5
	s_nop 0
	v_cndmask_b32_e32 v1, v1, v4, vcc
	v_mul_lo_u32 v4, v2, v1
	v_add_u32_e32 v2, v4, v2
	v_cmp_ne_u32_e32 vcc, v3, v2
	s_and_saveexec_b64 s[2:3], vcc
	s_xor_b64 s[2:3], exec, s[2:3]
	s_cbranch_execz .LBB0_1494
	s_waitcnt lgkmcnt(0)
	v_mov_b32_e32 v0, 0
	buffer_inv sc1
	global_load_dword v2, v0, s[68:69] sc1
	s_waitcnt vmcnt(0)
	v_cmp_eq_u32_e32 vcc, v2, v1
	s_and_saveexec_b64 s[4:5], vcc
	s_cbranch_execz .LBB0_1493
	s_mov_b32 s15, 1
	s_mov_b64 s[6:7], 0
	s_branch .LBB0_1484

.LBB0_1493:
	s_or_b64 exec, exec, s[4:5]
	s_waitcnt vmcnt(0)
	s_waitcnt vmcnt(0)

.LBB0_1511:
	s_or_b64 exec, exec, s[2:3]
	s_mov_b64 s[2:3], exec
	v_mbcnt_lo_u32_b32 v0, s2, 0
	v_mbcnt_hi_u32_b32 v0, s3, v0
	v_cmp_eq_u32_e32 vcc, 0, v0
	s_waitcnt vmcnt(0)
	s_and_saveexec_b64 s[4:5], vcc
	s_cbranch_execz .LBB0_1513
	s_bcnt1_i32_b64 s2, s[2:3]
	v_mov_b32_e32 v0, 0
	v_mov_b32_e32 v1, s2
	global_atomic_add v0, v1, s[68:69]
.LBB0_1513:
	s_or_b64 exec, exec, s[4:5]
	buffer_inv sc1
	s_waitcnt vmcnt(0)
